# rw_prepass stage 1 rewritten: loads batched, column groups handled with per-lane constants
# baseline (speedup 1.0000x reference)
.LBB0_175:
	s_add_i32 s0, s34, 0x4000
	s_mul_i32 s10, s0, 0x2600
	s_add_u32 s12, s14, s10
	v_readlane_b32 s10, v251, 21
	s_mul_hi_i32 s1, s0, 0x2600
	v_readlane_b32 s11, v251, 22
	s_addc_u32 s1, s15, s1
	s_lshl_b64 s[10:11], s[10:11], 1
	s_add_u32 s10, s12, s10
	s_addc_u32 s11, s1, s11
	v_lshl_add_u64 v[2:3], v[78:79], 1, s[10:11]
	s_movk_i32 s1, 0x1000
	v_add_co_u32_e32 v4, vcc, s1, v2
	s_movk_i32 s1, 0x3000
	s_nop 0
	v_addc_co_u32_e32 v5, vcc, 0, v3, vcc
	v_add_co_u32_e32 v6, vcc, s1, v2
	s_movk_i32 s12, 0x4000
	s_nop 0
	v_addc_co_u32_e32 v7, vcc, 0, v3, vcc
	v_add_co_u32_e32 v8, vcc, s12, v2
	s_movk_i32 s1, 0x6000
	s_nop 0
	v_addc_co_u32_e32 v9, vcc, 0, v3, vcc
	v_add_co_u32_e32 v10, vcc, s1, v2
	s_mov_b32 s1, 0x8000
	s_nop 0
	v_addc_co_u32_e32 v11, vcc, 0, v3, vcc
	v_add_co_u32_e32 v12, vcc, s1, v2
	s_mov_b64 s[10:11], 0x1800
	s_nop 0
	v_addc_co_u32_e32 v13, vcc, 0, v3, vcc
	s_mov_b32 s1, 0xb000
	v_lshl_add_u64 v[126:127], v[2:3], 0, s[10:11]
	global_load_ushort v219, v[4:5], off offset:2048
	global_load_ushort v217, v[6:7], off offset:3584
	global_load_ushort v218, v[8:9], off offset:512
	global_load_ushort v215, v[10:11], off offset:1024
	global_load_ushort v216, v[10:11], off offset:2048
	global_load_ushort v213, v[12:13], off offset:2560
	global_load_ushort v214, v[12:13], off offset:3584
	global_load_ushort v220, v[126:127], off offset:1024
	v_add_co_u32_e32 v4, vcc, s1, v2
	s_mov_b32 s1, 0xd000
	s_nop 0
	v_addc_co_u32_e32 v5, vcc, 0, v3, vcc
	v_add_co_u32_e32 v6, vcc, s1, v2
	s_mov_b32 s1, 0xf000
	s_nop 0
	v_addc_co_u32_e32 v7, vcc, 0, v3, vcc
	v_add_co_u32_e32 v8, vcc, s1, v2
	s_mov_b32 s1, 0x10000
	s_nop 0
	v_addc_co_u32_e32 v9, vcc, 0, v3, vcc
	v_add_co_u32_e32 v10, vcc, s1, v2
	s_mov_b32 s1, 0x12000
	s_nop 0
	v_addc_co_u32_e32 v11, vcc, 0, v3, vcc
	v_add_co_u32_e32 v12, vcc, s1, v2
	s_mov_b32 s1, 0x14000
	s_nop 0
	v_addc_co_u32_e32 v13, vcc, 0, v3, vcc
	global_load_ushort v211, v[4:5], off
	global_load_ushort v212, v[4:5], off offset:1024
	global_load_ushort v209, v[6:7], off offset:1536
	global_load_ushort v210, v[6:7], off offset:2560
	global_load_ushort v207, v[8:9], off offset:3072
	global_load_ushort v208, v[10:11], off
	global_load_ushort v205, v[12:13], off offset:512
	global_load_ushort v206, v[12:13], off offset:1536
	v_add_co_u32_e32 v4, vcc, s1, v2
	s_mov_b32 s1, 0x16000
	s_nop 0
	v_addc_co_u32_e32 v5, vcc, 0, v3, vcc
	v_add_co_u32_e32 v6, vcc, s1, v2
	s_mov_b32 s1, 0x17000
	s_nop 0
	v_addc_co_u32_e32 v7, vcc, 0, v3, vcc
	v_add_co_u32_e32 v8, vcc, s1, v2
	s_mov_b32 s1, 0x19000
	s_nop 0
	v_addc_co_u32_e32 v9, vcc, 0, v3, vcc
	v_add_co_u32_e32 v10, vcc, s1, v2
	s_mov_b32 s1, 0x1b000
	s_nop 0
	v_addc_co_u32_e32 v11, vcc, 0, v3, vcc
	v_add_co_u32_e32 v12, vcc, s1, v2
	s_mov_b32 s1, 0x1e000
	s_nop 0
	v_addc_co_u32_e32 v13, vcc, 0, v3, vcc
	global_load_ushort v203, v[4:5], off offset:2048
	global_load_ushort v204, v[4:5], off offset:3072
	global_load_ushort v201, v[6:7], off offset:3584
	global_load_ushort v202, v[8:9], off offset:512
	global_load_ushort v199, v[10:11], off offset:1024
	global_load_ushort v200, v[10:11], off offset:2048
	global_load_ushort v197, v[12:13], off offset:2560
	global_load_ushort v198, v[12:13], off offset:3584
	v_add_co_u32_e32 v4, vcc, s1, v2
	s_mov_b32 s1, 0x20000
	s_nop 0
	v_addc_co_u32_e32 v5, vcc, 0, v3, vcc
	v_add_co_u32_e32 v6, vcc, s1, v2
	s_mov_b32 s1, 0x22000
	s_nop 0
	v_addc_co_u32_e32 v7, vcc, 0, v3, vcc
	v_add_co_u32_e32 v8, vcc, s1, v2
	s_mov_b32 s1, 0x23000
	s_nop 0
	v_addc_co_u32_e32 v9, vcc, 0, v3, vcc
	v_add_co_u32_e32 v10, vcc, s1, v2
	s_mov_b32 s1, 0x25000
	s_nop 0
	v_addc_co_u32_e32 v11, vcc, 0, v3, vcc
	v_add_co_u32_e32 v2, vcc, s1, v2
	v_lshlrev_b32_e32 v0, 1, v80
	s_nop 0
	v_addc_co_u32_e32 v3, vcc, 0, v3, vcc
	global_load_ushort v195, v[4:5], off
	global_load_ushort v196, v[4:5], off offset:1024
	global_load_ushort v193, v[6:7], off offset:1536
	global_load_ushort v194, v[6:7], off offset:2560
	global_load_ushort v191, v[8:9], off offset:3072
	global_load_ushort v192, v[10:11], off
	global_load_ushort v189, v[2:3], off offset:512
	global_load_ushort v190, v[2:3], off offset:1536
	v_add_u32_e32 v8, s34, v152
	v_add_u32_e32 v9, 0x4000, v8
	v_mov_b64_e32 v[2:3], s[14:15]
	v_mad_i64_i32 v[2:3], s[10:11], v9, s79, v[2:3]
	v_lshl_add_u64 v[2:3], v[2:3], 0, v[0:1]
	v_add_co_u32_e32 v4, vcc, 0x2000, v2
	s_nop 1
	v_addc_co_u32_e32 v5, vcc, 0, v3, vcc
	s_barrier
	v_and_b32_e32 v0, 0x7ff, v9
	v_cmp_gt_i32_e32 vcc, s12, v9
	s_mov_b64 s[10:11], 0x2400
	s_movk_i32 s1, 0x3fff
	v_cndmask_b32_e32 v0, v153, v0, vcc
	v_lshl_add_u64 v[6:7], v[2:3], 0, s[10:11]
	v_cmp_ne_u32_e64 s[12:13], 0, v0
	v_cmp_lt_i32_e64 s[10:11], s1, v9
	v_lshrrev_b32_e32 v0, 2, v8
	v_mov_b64_e32 v[8:9], s[22:23]
	s_movk_i32 s1, 0x1c00
	v_mad_u64_u32 v[8:9], s[26:27], v0, s1, v[8:9]
	v_lshlrev_b32_e32 v0, 2, v80
	v_lshl_add_u64 v[8:9], v[8:9], 0, v[0:1]
	s_mov_b64 s[26:27], 0x1800
	v_lshl_add_u64 v[8:9], v[8:9], 0, s[26:27]
	s_andn2_b64 s[24:25], s[10:11], s[12:13]
	global_load_dwordx4 v[20:23], v[6:7], off
	global_load_dwordx4 v[24:27], v[6:7], off offset:16
	v_mov_b32_e32 v28, 0
	v_mov_b32_e32 v29, 0
	v_mov_b32_e32 v30, 0
	v_mov_b32_e32 v31, 0
	v_mov_b32_e32 v32, 0
	v_mov_b32_e32 v33, 0
	v_mov_b32_e32 v34, 0
	v_mov_b32_e32 v35, 0
	s_mov_b32 vcc_lo, 0xffffda00
	s_mov_b32 vcc_hi, -1
	v_lshl_add_u64 v[2:3], v[6:7], 0, vcc
	s_mov_b64 s[26:27], exec
	s_and_b64 exec, s[26:27], s[12:13]
	global_load_dwordx4 v[28:31], v[2:3], off
	global_load_dwordx4 v[32:35], v[2:3], off offset:16
	s_and_b64 exec, s[26:27], s[24:25]
	global_load_dwordx4 v[36:39], v[8:9], off
	global_load_dwordx4 v[40:43], v[8:9], off offset:16
	global_load_dwordx4 v[44:47], v[8:9], off offset:32
	global_load_dwordx4 v[48:51], v[8:9], off offset:48
	s_mov_b64 exec, s[26:27]
	global_load_dwordx4 v[52:55], v[82:83], off
	global_load_dwordx4 v[56:59], v[82:83], off offset:16
	global_load_dwordx4 v[60:63], v[82:83], off offset:32
	global_load_dwordx4 v[64:67], v[82:83], off offset:48
	s_andn2_b64 s[10:11], s[6:7], s[8:9]
	v_cndmask_b32_e64 v68, 2.0, 1.0, s[6:7]
	v_cndmask_b32_e64 v69, -1.0, 0, s[6:7]
	v_add_u32_e32 v70, 0x1180, v158
	v_cndmask_b32_e64 v70, v158, v70, s[6:7]
	v_add_u32_e32 v71, 0x2300, v157
	v_cndmask_b32_e64 v70, v70, v71, s[8:9]
	s_waitcnt vmcnt(0)
	v_lshlrev_b32_e32 v10, 16, v20
	v_and_b32_e32 v11, 0xffff0000, v20
	v_lshlrev_b32_e32 v12, 16, v21
	v_and_b32_e32 v13, 0xffff0000, v21
	v_lshlrev_b32_e32 v14, 16, v28
	v_and_b32_e32 v15, 0xffff0000, v28
	v_lshlrev_b32_e32 v16, 16, v29
	v_and_b32_e32 v17, 0xffff0000, v29
	v_cndmask_b32_e64 v14, v14, v36, s[24:25]
	v_cndmask_b32_e64 v15, v15, v37, s[24:25]
	v_cndmask_b32_e64 v16, v16, v38, s[24:25]
	v_cndmask_b32_e64 v17, v17, v39, s[24:25]
	v_sub_f32_e32 v14, v14, v10
	v_sub_f32_e32 v15, v15, v11
	v_sub_f32_e32 v16, v16, v12
	v_sub_f32_e32 v17, v17, v13
	v_pk_fma_f32 v[14:15], v[14:15], v[52:53], v[10:11]
	v_pk_fma_f32 v[16:17], v[16:17], v[54:55], v[12:13]
	v_mul_f32_e32 v10, v14, v68
	v_mul_f32_e32 v11, v15, v68
	v_mul_f32_e32 v12, v16, v68
	v_mul_f32_e32 v13, v17, v68
	v_mul_f32_e32 v10, 0xbfb8aa3b, v10
	v_mul_f32_e32 v11, 0xbfb8aa3b, v11
	v_mul_f32_e32 v12, 0xbfb8aa3b, v12
	v_mul_f32_e32 v13, 0xbfb8aa3b, v13
	v_exp_f32_e32 v10, v10
	v_exp_f32_e32 v11, v11
	v_exp_f32_e32 v12, v12
	v_exp_f32_e32 v13, v13
	v_add_f32_e32 v10, 1.0, v10
	v_add_f32_e32 v11, 1.0, v11
	v_add_f32_e32 v12, 1.0, v12
	v_add_f32_e32 v13, 1.0, v13
	v_rcp_f32_e32 v10, v10
	v_rcp_f32_e32 v11, v11
	v_rcp_f32_e32 v12, v12
	v_rcp_f32_e32 v13, v13
	v_fma_f32 v10, v10, v68, v69
	v_fma_f32 v11, v11, v68, v69
	v_fma_f32 v12, v12, v68, v69
	v_fma_f32 v13, v13, v68, v69
	v_cndmask_b32_e64 v10, v10, v14, s[10:11]
	v_cndmask_b32_e64 v11, v11, v15, s[10:11]
	v_cndmask_b32_e64 v12, v12, v16, s[10:11]
	v_cndmask_b32_e64 v13, v13, v17, s[10:11]
	v_cvt_pk_bf16_f32 v2, v10, v11
	v_cvt_pk_bf16_f32 v3, v12, v13
	ds_write_b64 v70, v[2:3]
	v_lshlrev_b32_e32 v10, 16, v22
	v_and_b32_e32 v11, 0xffff0000, v22
	v_lshlrev_b32_e32 v12, 16, v23
	v_and_b32_e32 v13, 0xffff0000, v23
	v_lshlrev_b32_e32 v14, 16, v30
	v_and_b32_e32 v15, 0xffff0000, v30
	v_lshlrev_b32_e32 v16, 16, v31
	v_and_b32_e32 v17, 0xffff0000, v31
	v_cndmask_b32_e64 v14, v14, v40, s[24:25]
	v_cndmask_b32_e64 v15, v15, v41, s[24:25]
	v_cndmask_b32_e64 v16, v16, v42, s[24:25]
	v_cndmask_b32_e64 v17, v17, v43, s[24:25]
	v_sub_f32_e32 v14, v14, v10
	v_sub_f32_e32 v15, v15, v11
	v_sub_f32_e32 v16, v16, v12
	v_sub_f32_e32 v17, v17, v13
	v_pk_fma_f32 v[14:15], v[14:15], v[56:57], v[10:11]
	v_pk_fma_f32 v[16:17], v[16:17], v[58:59], v[12:13]
	v_mul_f32_e32 v10, v14, v68
	v_mul_f32_e32 v11, v15, v68
	v_mul_f32_e32 v12, v16, v68
	v_mul_f32_e32 v13, v17, v68
	v_mul_f32_e32 v10, 0xbfb8aa3b, v10
	v_mul_f32_e32 v11, 0xbfb8aa3b, v11
	v_mul_f32_e32 v12, 0xbfb8aa3b, v12
	v_mul_f32_e32 v13, 0xbfb8aa3b, v13
	v_exp_f32_e32 v10, v10
	v_exp_f32_e32 v11, v11
	v_exp_f32_e32 v12, v12
	v_exp_f32_e32 v13, v13
	v_add_f32_e32 v10, 1.0, v10
	v_add_f32_e32 v11, 1.0, v11
	v_add_f32_e32 v12, 1.0, v12
	v_add_f32_e32 v13, 1.0, v13
	v_rcp_f32_e32 v10, v10
	v_rcp_f32_e32 v11, v11
	v_rcp_f32_e32 v12, v12
	v_rcp_f32_e32 v13, v13
	v_fma_f32 v10, v10, v68, v69
	v_fma_f32 v11, v11, v68, v69
	v_fma_f32 v12, v12, v68, v69
	v_fma_f32 v13, v13, v68, v69
	v_cndmask_b32_e64 v10, v10, v14, s[10:11]
	v_cndmask_b32_e64 v11, v11, v15, s[10:11]
	v_cndmask_b32_e64 v12, v12, v16, s[10:11]
	v_cndmask_b32_e64 v13, v13, v17, s[10:11]
	v_cvt_pk_bf16_f32 v2, v10, v11
	v_cvt_pk_bf16_f32 v3, v12, v13
	ds_write_b64 v70, v[2:3] offset:8
	v_lshlrev_b32_e32 v10, 16, v24
	v_and_b32_e32 v11, 0xffff0000, v24
	v_lshlrev_b32_e32 v12, 16, v25
	v_and_b32_e32 v13, 0xffff0000, v25
	v_lshlrev_b32_e32 v14, 16, v32
	v_and_b32_e32 v15, 0xffff0000, v32
	v_lshlrev_b32_e32 v16, 16, v33
	v_and_b32_e32 v17, 0xffff0000, v33
	v_cndmask_b32_e64 v14, v14, v44, s[24:25]
	v_cndmask_b32_e64 v15, v15, v45, s[24:25]
	v_cndmask_b32_e64 v16, v16, v46, s[24:25]
	v_cndmask_b32_e64 v17, v17, v47, s[24:25]
	v_sub_f32_e32 v14, v14, v10
	v_sub_f32_e32 v15, v15, v11
	v_sub_f32_e32 v16, v16, v12
	v_sub_f32_e32 v17, v17, v13
	v_pk_fma_f32 v[14:15], v[14:15], v[60:61], v[10:11]
	v_pk_fma_f32 v[16:17], v[16:17], v[62:63], v[12:13]
	v_mul_f32_e32 v10, v14, v68
	v_mul_f32_e32 v11, v15, v68
	v_mul_f32_e32 v12, v16, v68
	v_mul_f32_e32 v13, v17, v68
	v_mul_f32_e32 v10, 0xbfb8aa3b, v10
	v_mul_f32_e32 v11, 0xbfb8aa3b, v11
	v_mul_f32_e32 v12, 0xbfb8aa3b, v12
	v_mul_f32_e32 v13, 0xbfb8aa3b, v13
	v_exp_f32_e32 v10, v10
	v_exp_f32_e32 v11, v11
	v_exp_f32_e32 v12, v12
	v_exp_f32_e32 v13, v13
	v_add_f32_e32 v10, 1.0, v10
	v_add_f32_e32 v11, 1.0, v11
	v_add_f32_e32 v12, 1.0, v12
	v_add_f32_e32 v13, 1.0, v13
	v_rcp_f32_e32 v10, v10
	v_rcp_f32_e32 v11, v11
	v_rcp_f32_e32 v12, v12
	v_rcp_f32_e32 v13, v13
	v_fma_f32 v10, v10, v68, v69
	v_fma_f32 v11, v11, v68, v69
	v_fma_f32 v12, v12, v68, v69
	v_fma_f32 v13, v13, v68, v69
	v_cndmask_b32_e64 v10, v10, v14, s[10:11]
	v_cndmask_b32_e64 v11, v11, v15, s[10:11]
	v_cndmask_b32_e64 v12, v12, v16, s[10:11]
	v_cndmask_b32_e64 v13, v13, v17, s[10:11]
	v_cvt_pk_bf16_f32 v2, v10, v11
	v_cvt_pk_bf16_f32 v3, v12, v13
	ds_write_b64 v70, v[2:3] offset:16
	v_lshlrev_b32_e32 v10, 16, v26
	v_and_b32_e32 v11, 0xffff0000, v26
	v_lshlrev_b32_e32 v12, 16, v27
	v_and_b32_e32 v13, 0xffff0000, v27
	v_lshlrev_b32_e32 v14, 16, v34
	v_and_b32_e32 v15, 0xffff0000, v34
	v_lshlrev_b32_e32 v16, 16, v35
	v_and_b32_e32 v17, 0xffff0000, v35
	v_cndmask_b32_e64 v14, v14, v48, s[24:25]
	v_cndmask_b32_e64 v15, v15, v49, s[24:25]
	v_cndmask_b32_e64 v16, v16, v50, s[24:25]
	v_cndmask_b32_e64 v17, v17, v51, s[24:25]
	v_sub_f32_e32 v14, v14, v10
	v_sub_f32_e32 v15, v15, v11
	v_sub_f32_e32 v16, v16, v12
	v_sub_f32_e32 v17, v17, v13
	v_pk_fma_f32 v[14:15], v[14:15], v[64:65], v[10:11]
	v_pk_fma_f32 v[16:17], v[16:17], v[66:67], v[12:13]
	v_mul_f32_e32 v10, v14, v68
	v_mul_f32_e32 v11, v15, v68
	v_mul_f32_e32 v12, v16, v68
	v_mul_f32_e32 v13, v17, v68
	v_mul_f32_e32 v10, 0xbfb8aa3b, v10
	v_mul_f32_e32 v11, 0xbfb8aa3b, v11
	v_mul_f32_e32 v12, 0xbfb8aa3b, v12
	v_mul_f32_e32 v13, 0xbfb8aa3b, v13
	v_exp_f32_e32 v10, v10
	v_exp_f32_e32 v11, v11
	v_exp_f32_e32 v12, v12
	v_exp_f32_e32 v13, v13
	v_add_f32_e32 v10, 1.0, v10
	v_add_f32_e32 v11, 1.0, v11
	v_add_f32_e32 v12, 1.0, v12
	v_add_f32_e32 v13, 1.0, v13
	v_rcp_f32_e32 v10, v10
	v_rcp_f32_e32 v11, v11
	v_rcp_f32_e32 v12, v12
	v_rcp_f32_e32 v13, v13
	v_fma_f32 v10, v10, v68, v69
	v_fma_f32 v11, v11, v68, v69
	v_fma_f32 v12, v12, v68, v69
	v_fma_f32 v13, v13, v68, v69
	v_cndmask_b32_e64 v10, v10, v14, s[10:11]
	v_cndmask_b32_e64 v11, v11, v15, s[10:11]
	v_cndmask_b32_e64 v12, v12, v16, s[10:11]
	v_cndmask_b32_e64 v13, v13, v17, s[10:11]
	v_cvt_pk_bf16_f32 v2, v10, v11
	v_cvt_pk_bf16_f32 v3, v12, v13
	ds_write_b64 v70, v[2:3] offset:24
